# attention: K/V piece addresses kept phase-constant with a scalar tile offset, the two freed register quads give PV eight V-fragment buffers in flight instead of six; on top of v43
# baseline (speedup 1.0000x reference)
; #define LAS __attribute__((address_space(3)))
; __device__ __forceinline__ unsigned cvtpk(float lo, float hi) { return pg8::cvt_pk_bf16(lo, hi); }
; __device__ __forceinline__ float bflo(unsigned u) { return __uint_as_float(u << 16); }
; __device__ __forceinline__ float bfhi(unsigned u) { return __uint_as_float(u & 0xffff0000u); }
; __device__ __forceinline__ void attn_phase(LAS unsigned char* lds, const bf16_t* proj, bf16_t* oa, const float* lamp, const float* subg, const float* relb, const float* qg, int wg, int tid) {
;     ...
;         const int qb = (ui == 0) ? sx : (ui == 1) ? 15 - sx : (ui == 2) ? 16 + sx : 31 - sx;
;         const int q0 = qb * 128, qw0 = q0 + wave * 16, nkt = (q0 + 128) / 32;
;         LAS bf16_t* Qw = Qs + wave * (2 * 16 * KP);
; #pragma unroll
;         for (int s = 0; s < 2; ++s) { u32x4 qc[4]; float ss = 0.f;
; #pragma unroll
;             for (int ks = 0; ks < 4; ++ks) { qc[ks] = *(const u32x4*)(proj + (rb + qw0 + fr) * DIFF_IN + (2 * h + s) * 128 + 32 * ks + 8 * fq);
; #pragma unroll
;                 for (int e = 0; e < 4; ++e) { const float a = bflo(qc[ks][e]), c = bfhi(qc[ks][e]); ss += a * a + c * c; } }
;             ss += __shfl_xor(ss, 16); ss += __shfl_xor(ss, 32);
;             const float rs = (1.0f / sqrtf(ss * (1.f / 128.f) + EPS)) * QSCALE;
; #pragma unroll
;             for (int ks = 0; ks < 4; ++ks) { const f32x4 g0 = *(const f32x4*)(qg + 32 * ks + 8 * fq), g1 = *(const f32x4*)(qg + 32 * ks + 8 * fq + 4);
;                 u32x4 o; o.x = cvtpk(bflo(qc[ks].x) * rs * g0[0], bfhi(qc[ks].x) * rs * g0[1]); o.y = cvtpk(bflo(qc[ks].y) * rs * g0[2], bfhi(qc[ks].y) * rs * g0[3]);
;                 o.z = cvtpk(bflo(qc[ks].z) * rs * g1[0], bfhi(qc[ks].z) * rs * g1[1]); o.w = cvtpk(bflo(qc[ks].w) * rs * g1[2], bfhi(qc[ks].w) * rs * g1[3]);
;                 *(LAS u32x4*)(Qw + (s * 16 + fr) * KP + 32 * ks + 8 * fq) = o; } }
.LBB0_593:
	s_lshl_b32 s0, s20, 7
	s_add_i32 s40, s0, s6
	s_ashr_i32 s41, s40, 31
	v_lshl_add_u64 v[18:19], v[168:169], 0, s[40:41]
	v_mad_u64_u32 v[58:59], s[20:21], v18, s28, v[200:201]
	v_mov_b32_e32 v0, v59
	v_mad_u64_u32 v[18:19], s[20:21], v19, s28, v[0:1]
	v_mov_b32_e32 v59, v18
	global_load_dwordx4 v[38:41], v[58:59], off offset:192
	global_load_dwordx4 v[42:45], v[58:59], off
	global_load_dwordx4 v[46:49], v[58:59], off offset:64
	global_load_dwordx4 v[84:87], v[58:59], off offset:128
	global_load_dwordx4 v[18:21], v[170:171], off offset:16
	global_load_dwordx4 v[22:25], v[170:171], off
	global_load_dwordx4 v[26:29], v[170:171], off offset:144
	global_load_dwordx4 v[30:33], v[170:171], off offset:128
	global_load_dwordx4 v[34:37], v[170:171], off offset:256
	s_add_i32 s20, s0, 0x80
	s_mov_b32 s33, 1
	s_lshr_b32 s34, s20, 5
	s_or_b32 s35, s40, 15
	s_sub_i32 s36, s40, 31
	s_mov_b32 s37, 0
	s_mov_b64 s[100:101], s[72:73]
	s_waitcnt vmcnt(8)
	v_and_b32_e32 v57, 0xffff0000, v39
	s_waitcnt vmcnt(7)
	v_lshlrev_b32_e32 v76, 16, v45
	v_and_b32_e32 v77, 0xffff0000, v45
	v_lshlrev_b32_e32 v80, 16, v43
	v_and_b32_e32 v81, 0xffff0000, v43
	v_lshlrev_b32_e32 v82, 16, v42
	v_and_b32_e32 v83, 0xffff0000, v42
	v_lshlrev_b32_e32 v78, 16, v44
	v_and_b32_e32 v79, 0xffff0000, v44
	s_waitcnt vmcnt(6)
	v_lshlrev_b32_e32 v64, 16, v49
	v_and_b32_e32 v65, 0xffff0000, v49
	v_lshlrev_b32_e32 v68, 16, v48
	v_and_b32_e32 v69, 0xffff0000, v48
	v_lshlrev_b32_e32 v72, 16, v47
	v_and_b32_e32 v73, 0xffff0000, v47
	v_lshlrev_b32_e32 v74, 16, v46
	v_and_b32_e32 v75, 0xffff0000, v46
	v_pk_mul_f32 v[42:43], v[76:77], v[76:77]
	v_pk_mul_f32 v[46:47], v[80:81], v[80:81]
	v_pk_mul_f32 v[48:49], v[82:83], v[82:83]
	v_pk_mul_f32 v[44:45], v[78:79], v[78:79]
	v_add_f32_e32 v0, v42, v43
	v_add_f32_e32 v42, v46, v47
	v_add_f32_e32 v43, v48, v49
	v_add_f32_e32 v44, v44, v45
	v_add_f32_e32 v42, v43, v42
	v_pk_mul_f32 v[90:91], v[74:75], v[74:75]
	v_add_f32_e32 v42, v44, v42
	v_pk_mul_f32 v[88:89], v[72:73], v[72:73]
	v_add_f32_e32 v45, v90, v91
	v_add_f32_e32 v0, v0, v42
	s_waitcnt vmcnt(5)
	v_lshlrev_b32_e32 v60, 16, v87
	v_and_b32_e32 v61, 0xffff0000, v87
	v_lshlrev_b32_e32 v62, 16, v86
	v_and_b32_e32 v63, 0xffff0000, v86
	v_pk_mul_f32 v[86:87], v[68:69], v[68:69]
	v_add_f32_e32 v46, v88, v89
	v_add_f32_e32 v0, v45, v0
	v_lshlrev_b32_e32 v66, 16, v85
	v_and_b32_e32 v67, 0xffff0000, v85
	v_lshlrev_b32_e32 v70, 16, v84
	v_and_b32_e32 v71, 0xffff0000, v84
	v_pk_mul_f32 v[84:85], v[64:65], v[64:65]
	v_add_f32_e32 v47, v86, v87
	v_add_f32_e32 v0, v46, v0
	v_pk_mul_f32 v[98:99], v[70:71], v[70:71]
	v_add_f32_e32 v48, v84, v85
	v_add_f32_e32 v0, v47, v0
	v_pk_mul_f32 v[96:97], v[66:67], v[66:67]
	v_add_f32_e32 v49, v98, v99
	v_add_f32_e32 v0, v48, v0
	v_pk_mul_f32 v[94:95], v[62:63], v[62:63]
	v_add_f32_e32 v84, v96, v97
	v_add_f32_e32 v0, v49, v0
	v_and_b32_e32 v56, 0xffff0000, v38
	v_pk_mul_f32 v[92:93], v[60:61], v[60:61]
	v_add_f32_e32 v85, v94, v95
	v_add_f32_e32 v0, v84, v0
	v_lshlrev_b32_e32 v55, 16, v39
	v_lshlrev_b32_e32 v54, 16, v38
	v_pk_mul_f32 v[38:39], v[56:57], v[56:57]
	v_add_f32_e32 v86, v92, v93
	v_add_f32_e32 v0, v85, v0
	v_and_b32_e32 v53, 0xffff0000, v41
	v_and_b32_e32 v52, 0xffff0000, v40
	v_pk_fma_f32 v[38:39], v[54:55], v[54:55], v[38:39]
	v_add_f32_e32 v0, v86, v0
	v_lshlrev_b32_e32 v51, 16, v41
	v_lshlrev_b32_e32 v50, 16, v40
	v_pk_mul_f32 v[40:41], v[52:53], v[52:53]
	v_add_f32_e32 v0, v38, v0
	v_pk_fma_f32 v[40:41], v[50:51], v[50:51], v[40:41]
	v_add_f32_e32 v0, v39, v0
	v_add_f32_e32 v0, v40, v0
	v_add_f32_e32 v0, v41, v0
	ds_bpermute_b32 v42, v232, v0
	global_load_dwordx4 v[38:41], v[170:171], off offset:272
	s_waitcnt lgkmcnt(0)
	v_add_f32_e32 v0, v0, v42
	ds_bpermute_b32 v92, v233, v0
	global_load_dwordx4 v[42:45], v[170:171], off offset:400
	global_load_dwordx4 v[46:49], v[170:171], off offset:384
	global_load_dwordx4 v[84:87], v[58:59], off offset:384
	global_load_dwordx4 v[88:91], v[58:59], off offset:448
	s_waitcnt lgkmcnt(0)
	v_add_f32_e32 v0, v0, v92
	v_fmamk_f32 v0, v0, 0x3c000000, v189
	v_mul_f32_e32 v92, 0x4f800000, v0
	v_cmp_gt_f32_e32 vcc, s22, v0
	s_waitcnt vmcnt(1)
	v_lshlrev_b32_e32 v116, 16, v84
	v_cndmask_b32_e32 v0, v0, v92, vcc
	v_sqrt_f32_e32 v96, v0
	global_load_dwordx4 v[92:95], v[58:59], off offset:256
	v_and_b32_e32 v117, 0xffff0000, v84
	v_lshlrev_b32_e32 v112, 16, v85
	v_add_u32_e32 v97, -1, v96
	v_add_u32_e32 v98, 1, v96
	v_fma_f32 v99, -v97, v96, v0
	v_fma_f32 v100, -v98, v96, v0
	v_cmp_ge_f32_e64 s[0:1], 0, v99
	v_and_b32_e32 v113, 0xffff0000, v85
	v_pk_mul_f32 v[84:85], v[116:117], v[116:117]
	v_cndmask_b32_e64 v96, v96, v97, s[0:1]
	v_cmp_lt_f32_e64 s[0:1], 0, v100
	v_lshlrev_b32_e32 v110, 16, v86
	v_and_b32_e32 v111, 0xffff0000, v86
	v_cndmask_b32_e64 v96, v96, v98, s[0:1]
	v_mul_f32_e32 v97, 0x37800000, v96
	v_cndmask_b32_e32 v96, v96, v97, vcc
	v_cmp_class_f32_e32 vcc, v0, v191
	v_pk_mul_f32 v[114:115], v[112:113], v[112:113]
	v_lshlrev_b32_e32 v106, 16, v87
	v_cndmask_b32_e32 v0, v96, v0, vcc
	global_load_dwordx4 v[96:99], v[58:59], off offset:320
	v_div_scale_f32 v100, s[0:1], v0, v0, 1.0
	v_rcp_f32_e32 v101, v100
	v_div_scale_f32 v58, vcc, 1.0, v0, 1.0
	v_and_b32_e32 v107, 0xffff0000, v87
	v_fma_f32 v59, -v100, v101, 1.0
	v_fmac_f32_e32 v101, v59, v101
	v_mul_f32_e32 v59, v58, v101
	v_fma_f32 v102, -v100, v59, v58
	v_fmac_f32_e32 v59, v102, v101
	v_fma_f32 v58, -v100, v59, v58
	v_div_fmas_f32 v58, v58, v101, v59
	v_div_fixup_f32 v0, v58, v0, 1.0
	v_mul_f32_e32 v0, 0x3e0293ee, v0
	v_pk_mul_f32 v[58:59], v[0:1], v[82:83] op_sel_hi:[0,1]
	v_pk_mul_f32 v[78:79], v[0:1], v[78:79] op_sel_hi:[0,1]
; #define LAS __attribute__((address_space(3)))
; __device__ __forceinline__ unsigned cvtpk(float lo, float hi) { return pg8::cvt_pk_bf16(lo, hi); }
; __device__ __forceinline__ float bflo(unsigned u) { return __uint_as_float(u << 16); }
; __device__ __forceinline__ float bfhi(unsigned u) { return __uint_as_float(u & 0xffff0000u); }
; __device__ __forceinline__ void attn_phase(LAS unsigned char* lds, const bf16_t* proj, bf16_t* oa, const float* lamp, const float* subg, const float* relb, const float* qg, int wg, int tid) {
;     ...
;         for (int s = 0; s < 2; ++s) { u32x4 qc[4]; float ss = 0.f;
; #pragma unroll
;             for (int ks = 0; ks < 4; ++ks) { qc[ks] = *(const u32x4*)(proj + (rb + qw0 + fr) * DIFF_IN + (2 * h + s) * 128 + 32 * ks + 8 * fq);
; #pragma unroll
;                 for (int e = 0; e < 4; ++e) { const float a = bflo(qc[ks][e]), c = bfhi(qc[ks][e]); ss += a * a + c * c; } }
;             ss += __shfl_xor(ss, 16); ss += __shfl_xor(ss, 32);
;             const float rs = (1.0f / sqrtf(ss * (1.f / 128.f) + EPS)) * QSCALE;
; #pragma unroll
;             for (int ks = 0; ks < 4; ++ks) { const f32x4 g0 = *(const f32x4*)(qg + 32 * ks + 8 * fq), g1 = *(const f32x4*)(qg + 32 * ks + 8 * fq + 4);
;                 u32x4 o; o.x = cvtpk(bflo(qc[ks].x) * rs * g0[0], bfhi(qc[ks].x) * rs * g0[1]); o.y = cvtpk(bflo(qc[ks].y) * rs * g0[2], bfhi(qc[ks].y) * rs * g0[3]);
;                 o.z = cvtpk(bflo(qc[ks].z) * rs * g1[0], bfhi(qc[ks].z) * rs * g1[1]); o.w = cvtpk(bflo(qc[ks].w) * rs * g1[2], bfhi(qc[ks].w) * rs * g1[3]);
;                 *(LAS u32x4*)(Qw + (s * 16 + fr) * KP + 32 * ks + 8 * fq) = o; } }
	v_pk_mul_f32 v[82:83], v[0:1], v[76:77] op_sel_hi:[0,1]
	v_pk_mul_f32 v[58:59], v[22:23], v[58:59]
	v_pk_mul_f32 v[78:79], v[18:19], v[78:79]
	v_cvt_pk_bf16_f32 v76, v58, v59
	v_pk_mul_f32 v[58:59], v[20:21], v[82:83]
	v_cvt_pk_bf16_f32 v78, v78, v79
	v_cvt_pk_bf16_f32 v79, v58, v59
	v_pk_mul_f32 v[58:59], v[0:1], v[74:75] op_sel_hi:[0,1]
	v_pk_mul_f32 v[58:59], v[30:31], v[58:59]
	v_pk_mul_f32 v[80:81], v[0:1], v[80:81] op_sel_hi:[0,1]
	v_cvt_pk_bf16_f32 v74, v58, v59
	v_pk_mul_f32 v[58:59], v[0:1], v[72:73] op_sel_hi:[0,1]
	v_pk_mul_f32 v[58:59], v[32:33], v[58:59]
	v_pk_mul_f32 v[80:81], v[24:25], v[80:81]
	v_cvt_pk_bf16_f32 v75, v58, v59
	v_pk_mul_f32 v[58:59], v[0:1], v[68:69] op_sel_hi:[0,1]
	v_cvt_pk_bf16_f32 v77, v80, v81
	v_pk_mul_f32 v[58:59], v[26:27], v[58:59]
	ds_write_b128 v248, v[76:79]
	v_cvt_pk_bf16_f32 v76, v58, v59
	v_pk_mul_f32 v[58:59], v[0:1], v[64:65] op_sel_hi:[0,1]
	v_pk_mul_f32 v[58:59], v[28:29], v[58:59]
	v_pk_mul_f32 v[86:87], v[110:111], v[110:111]
	v_cvt_pk_bf16_f32 v77, v58, v59
	v_pk_mul_f32 v[58:59], v[0:1], v[70:71] op_sel_hi:[0,1]
	v_pk_mul_f32 v[58:59], v[34:35], v[58:59]
	ds_write_b128 v248, v[74:77] offset:64
	v_cvt_pk_bf16_f32 v64, v58, v59
	v_pk_mul_f32 v[58:59], v[0:1], v[66:67] op_sel_hi:[0,1]
	v_pk_mul_f32 v[58:59], v[36:37], v[58:59]
	v_pk_mul_f32 v[108:109], v[106:107], v[106:107]
	v_cvt_pk_bf16_f32 v65, v58, v59
	v_pk_mul_f32 v[58:59], v[0:1], v[62:63] op_sel_hi:[0,1]
	v_pk_mul_f32 v[58:59], v[38:39], v[58:59]
	s_waitcnt vmcnt(2)
	v_and_b32_e32 v63, 0xffff0000, v89
	v_cvt_pk_bf16_f32 v66, v58, v59
	v_pk_mul_f32 v[58:59], v[0:1], v[60:61] op_sel_hi:[0,1]
	v_pk_mul_f32 v[58:59], v[40:41], v[58:59]
	v_and_b32_e32 v62, 0xffff0000, v88
	v_cvt_pk_bf16_f32 v67, v58, v59
	v_mov_b32_e32 v58, v54
	v_mov_b32_e32 v59, v56
	v_pk_mul_f32 v[58:59], v[0:1], v[58:59] op_sel_hi:[0,1]
	v_pk_mul_f32 v[58:59], v[46:47], v[58:59]
	s_waitcnt vmcnt(1)
	v_lshlrev_b32_e32 v78, 16, v95
	v_cvt_pk_bf16_f32 v54, v58, v59
	v_lshlrev_b32_e32 v59, 16, v89
	v_lshlrev_b32_e32 v58, 16, v88
	v_and_b32_e32 v79, 0xffff0000, v95
	v_lshlrev_b32_e32 v82, 16, v93
	v_and_b32_e32 v83, 0xffff0000, v93
	v_lshlrev_b32_e32 v88, 16, v92
	v_and_b32_e32 v89, 0xffff0000, v92
	v_pk_mul_f32 v[70:71], v[78:79], v[78:79]
	v_lshlrev_b32_e32 v80, 16, v94
	v_and_b32_e32 v81, 0xffff0000, v94
	v_pk_mul_f32 v[74:75], v[82:83], v[82:83]
	v_pk_mul_f32 v[76:77], v[88:89], v[88:89]
	v_pk_mul_f32 v[72:73], v[80:81], v[80:81]
	v_add_f32_e32 v56, v70, v71
	v_add_f32_e32 v70, v74, v75
	v_add_f32_e32 v71, v76, v77
	s_waitcnt vmcnt(0)
	v_lshlrev_b32_e32 v104, 16, v96
	v_and_b32_e32 v105, 0xffff0000, v96
	v_add_f32_e32 v70, v71, v70
	v_add_f32_e32 v71, v72, v73
	v_lshlrev_b32_e32 v100, 16, v97
	v_and_b32_e32 v101, 0xffff0000, v97
	v_pk_mul_f32 v[96:97], v[104:105], v[104:105]
	v_add_f32_e32 v70, v71, v70
	v_pk_mul_f32 v[60:61], v[62:63], v[62:63]
	v_lshlrev_b32_e32 v94, 16, v98
	v_and_b32_e32 v95, 0xffff0000, v98
	v_pk_mul_f32 v[102:103], v[100:101], v[100:101]
	v_add_f32_e32 v56, v56, v70
	v_add_f32_e32 v70, v96, v97
	ds_write_b128 v248, v[64:67] offset:128
	v_pk_fma_f32 v[66:67], v[58:59], v[58:59], v[60:61]
	v_lshlrev_b32_e32 v61, 16, v91
	v_lshlrev_b32_e32 v60, 16, v90
	v_and_b32_e32 v65, 0xffff0000, v91
	v_and_b32_e32 v64, 0xffff0000, v90
	v_lshlrev_b32_e32 v90, 16, v99
	v_and_b32_e32 v91, 0xffff0000, v99
	v_pk_mul_f32 v[98:99], v[94:95], v[94:95]
	v_add_f32_e32 v56, v70, v56
	v_add_f32_e32 v70, v102, v103
	v_pk_mul_f32 v[92:93], v[90:91], v[90:91]
	v_add_f32_e32 v56, v70, v56
	v_add_f32_e32 v70, v98, v99
	v_add_f32_e32 v56, v70, v56
	v_add_f32_e32 v70, v92, v93
	v_add_f32_e32 v56, v70, v56
	v_add_f32_e32 v70, v84, v85
	v_add_f32_e32 v56, v70, v56
	v_add_f32_e32 v70, v114, v115
	v_add_f32_e32 v56, v70, v56
	v_add_f32_e32 v70, v86, v87
	v_add_f32_e32 v56, v70, v56
	v_add_f32_e32 v70, v108, v109
	v_add_f32_e32 v56, v70, v56
	v_pk_mul_f32 v[68:69], v[64:65], v[64:65]
	v_add_f32_e32 v56, v66, v56
	v_pk_fma_f32 v[68:69], v[60:61], v[60:61], v[68:69]
	v_add_f32_e32 v56, v67, v56
	v_add_f32_e32 v56, v68, v56
	v_add_f32_e32 v66, v69, v56
	ds_bpermute_b32 v67, v232, v66
	v_mov_b32_e32 v56, v55
	v_pk_mul_f32 v[56:57], v[0:1], v[56:57] op_sel_hi:[0,1]
	v_pk_mul_f32 v[56:57], v[48:49], v[56:57]
	s_waitcnt lgkmcnt(0)
	v_add_f32_e32 v66, v66, v67
	ds_bpermute_b32 v67, v233, v66
	v_cvt_pk_bf16_f32 v55, v56, v57
	v_mov_b32_e32 v56, v50
	v_mov_b32_e32 v57, v52
	v_pk_mul_f32 v[56:57], v[0:1], v[56:57] op_sel_hi:[0,1]
	s_waitcnt lgkmcnt(0)
; #define LAS __attribute__((address_space(3)))
; __device__ __forceinline__ unsigned cvtpk(float lo, float hi) { return pg8::cvt_pk_bf16(lo, hi); }
; __device__ __forceinline__ float bflo(unsigned u) { return __uint_as_float(u << 16); }
; __device__ __forceinline__ float bfhi(unsigned u) { return __uint_as_float(u & 0xffff0000u); }
; __device__ __forceinline__ void attn_phase(LAS unsigned char* lds, const bf16_t* proj, bf16_t* oa, const float* lamp, const float* subg, const float* relb, const float* qg, int wg, int tid) {
;     ...
;             ss += __shfl_xor(ss, 16); ss += __shfl_xor(ss, 32);
;             const float rs = (1.0f / sqrtf(ss * (1.f / 128.f) + EPS)) * QSCALE;
; #pragma unroll
;             for (int ks = 0; ks < 4; ++ks) { const f32x4 g0 = *(const f32x4*)(qg + 32 * ks + 8 * fq), g1 = *(const f32x4*)(qg + 32 * ks + 8 * fq + 4);
;                 u32x4 o; o.x = cvtpk(bflo(qc[ks].x) * rs * g0[0], bfhi(qc[ks].x) * rs * g0[1]); o.y = cvtpk(bflo(qc[ks].y) * rs * g0[2], bfhi(qc[ks].y) * rs * g0[3]);
;                 o.z = cvtpk(bflo(qc[ks].z) * rs * g1[0], bfhi(qc[ks].z) * rs * g1[1]); o.w = cvtpk(bflo(qc[ks].w) * rs * g1[2], bfhi(qc[ks].w) * rs * g1[3]);
;                 *(LAS u32x4*)(Qw + (s * 16 + fr) * KP + 32 * ks + 8 * fq) = o; } }
; #pragma unroll
;         for (int i = 0; i < 2; ++i) { const int id = tid + 512 * i, s = id >> 9, row = (id >> 4) & 31, ch = id & 15;
;             *(LAS u32x4*)(Kb + (s * 32 + row) * KP + ch * 8) = *(const u32x4*)(ksrc + (size_t)row * DIFF_IN + s * 128 + ch * 8); }
; #pragma unroll
;         for (int i = 0; i < 2; ++i) { const int id = tid + 512 * i, row = id >> 5, ch = id & 31;
;             *(LAS u32x4*)(Vb + row * VP + ch * 8) = *(const u32x4*)(vsrc + (size_t)row * DIFF_IN + ch * 8); }
;         __syncthreads();
;         float l0 = 0.f, l1 = 0.f;
;         f32x4 o[2][16];
; #pragma unroll
;         for (int s = 0; s < 2; ++s)
; #pragma unroll
;             for (int vt = 0; vt < 16; ++vt) o[s][vt] = (f32x4){0.f, 0.f, 0.f, 0.f};
	v_add_f32_e32 v50, v66, v67
	v_fmamk_f32 v50, v50, 0x3c000000, v189
	v_mul_f32_e32 v52, 0x4f800000, v50
	v_cmp_gt_f32_e32 vcc, s22, v50
	v_pk_mul_f32 v[56:57], v[42:43], v[56:57]
	s_nop 0
	v_cndmask_b32_e32 v50, v50, v52, vcc
	v_sqrt_f32_e32 v66, v50
	v_mov_b32_e32 v52, v51
	v_pk_mul_f32 v[84:85], v[0:1], v[52:53] op_sel_hi:[0,1]
	v_pk_mul_f32 v[84:85], v[44:45], v[84:85]
	v_add_u32_e32 v0, -1, v66
	v_fma_f32 v51, -v0, v66, v50
	v_cmp_ge_f32_e64 s[0:1], 0, v51
	v_add_u32_e32 v51, 1, v66
	v_fma_f32 v52, -v51, v66, v50
	v_cndmask_b32_e64 v0, v66, v0, s[0:1]
	v_cmp_lt_f32_e64 s[0:1], 0, v52
	v_cvt_pk_bf16_f32 v56, v56, v57
	v_cvt_pk_bf16_f32 v57, v84, v85
	v_cndmask_b32_e64 v0, v0, v51, s[0:1]
	v_mul_f32_e32 v51, 0x37800000, v0
	v_cndmask_b32_e32 v0, v0, v51, vcc
	v_cmp_class_f32_e32 vcc, v50, v191
	s_nop 1
	v_cndmask_b32_e32 v0, v0, v50, vcc
	global_load_dwordx4 v[50:53], v[178:179], off
	global_load_dwordx4 v[66:69], v[180:181], off
	global_load_dwordx4 v[70:73], v[182:183], off
	global_load_dwordx4 v[74:77], v[184:185], off
	v_div_scale_f32 v86, s[0:1], v0, v0, 1.0
	v_rcp_f32_e32 v87, v86
	ds_write_b128 v248, v[54:57] offset:192
	v_fma_f32 v54, -v86, v87, 1.0
	v_fmac_f32_e32 v87, v54, v87
	v_div_scale_f32 v54, vcc, 1.0, v0, 1.0
	v_mul_f32_e32 v55, v54, v87
	v_fma_f32 v56, -v86, v55, v54
	v_fmac_f32_e32 v55, v56, v87
	v_fma_f32 v54, -v86, v55, v54
	v_div_fmas_f32 v54, v54, v87, v55
	v_div_fixup_f32 v0, v54, v0, 1.0
	v_mul_f32_e32 v0, 0x3e0293ee, v0
	v_pk_mul_f32 v[54:55], v[0:1], v[88:89] op_sel_hi:[0,1]
	v_pk_mul_f32 v[22:23], v[22:23], v[54:55]
	v_pk_mul_f32 v[54:55], v[0:1], v[82:83] op_sel_hi:[0,1]
	v_pk_mul_f32 v[24:25], v[24:25], v[54:55]
	v_cvt_pk_bf16_f32 v22, v22, v23
	v_cvt_pk_bf16_f32 v23, v24, v25
	v_pk_mul_f32 v[24:25], v[0:1], v[80:81] op_sel_hi:[0,1]
	v_pk_mul_f32 v[18:19], v[18:19], v[24:25]
	s_nop 0
	v_cvt_pk_bf16_f32 v24, v18, v19
	v_pk_mul_f32 v[18:19], v[0:1], v[78:79] op_sel_hi:[0,1]
	v_pk_mul_f32 v[18:19], v[20:21], v[18:19]
	v_pk_mul_f32 v[20:21], v[0:1], v[100:101] op_sel_hi:[0,1]
	v_cvt_pk_bf16_f32 v25, v18, v19
	v_pk_mul_f32 v[18:19], v[0:1], v[104:105] op_sel_hi:[0,1]
	v_pk_mul_f32 v[18:19], v[30:31], v[18:19]
	v_pk_mul_f32 v[20:21], v[32:33], v[20:21]
	ds_write_b128 v248, v[22:25] offset:4608
	v_cvt_pk_bf16_f32 v18, v18, v19
	v_cvt_pk_bf16_f32 v19, v20, v21
	v_pk_mul_f32 v[20:21], v[0:1], v[94:95] op_sel_hi:[0,1]
	v_pk_mul_f32 v[22:23], v[0:1], v[90:91] op_sel_hi:[0,1]
	v_pk_mul_f32 v[20:21], v[26:27], v[20:21]
	v_pk_mul_f32 v[22:23], v[28:29], v[22:23]
	v_cvt_pk_bf16_f32 v20, v20, v21
	v_cvt_pk_bf16_f32 v21, v22, v23
	ds_write_b128 v248, v[18:21] offset:4672
	v_pk_mul_f32 v[18:19], v[0:1], v[116:117] op_sel_hi:[0,1]
	v_pk_mul_f32 v[20:21], v[0:1], v[112:113] op_sel_hi:[0,1]
	v_pk_mul_f32 v[18:19], v[34:35], v[18:19]
	v_pk_mul_f32 v[20:21], v[36:37], v[20:21]
	v_cvt_pk_bf16_f32 v18, v18, v19
	v_cvt_pk_bf16_f32 v19, v20, v21
	v_pk_mul_f32 v[20:21], v[0:1], v[110:111] op_sel_hi:[0,1]
	v_pk_mul_f32 v[22:23], v[0:1], v[106:107] op_sel_hi:[0,1]
	v_pk_mul_f32 v[20:21], v[38:39], v[20:21]
	v_pk_mul_f32 v[22:23], v[40:41], v[22:23]
	v_cvt_pk_bf16_f32 v20, v20, v21
	v_cvt_pk_bf16_f32 v21, v22, v23
	ds_write_b128 v248, v[18:21] offset:4736
	v_mov_b32_e32 v18, v58
	v_mov_b32_e32 v19, v62
	v_mov_b32_e32 v62, v59
	v_pk_mul_f32 v[18:19], v[0:1], v[18:19] op_sel_hi:[0,1]
	v_pk_mul_f32 v[20:21], v[0:1], v[62:63] op_sel_hi:[0,1]
	v_pk_mul_f32 v[18:19], v[46:47], v[18:19]
	v_pk_mul_f32 v[20:21], v[48:49], v[20:21]
	v_cvt_pk_bf16_f32 v18, v18, v19
	v_cvt_pk_bf16_f32 v19, v20, v21
	v_mov_b32_e32 v20, v60
	v_mov_b32_e32 v21, v64
	v_mov_b32_e32 v64, v61
	v_pk_mul_f32 v[20:21], v[0:1], v[20:21] op_sel_hi:[0,1]
	v_pk_mul_f32 v[22:23], v[0:1], v[64:65] op_sel_hi:[0,1]
	v_pk_mul_f32 v[20:21], v[42:43], v[20:21]
	v_pk_mul_f32 v[22:23], v[44:45], v[22:23]
	v_cvt_pk_bf16_f32 v20, v20, v21
	v_cvt_pk_bf16_f32 v21, v22, v23
	v_add_u32_e32 v0, v235, v237
	ds_write_b128 v248, v[18:21] offset:4800
	s_waitcnt vmcnt(3)
	ds_write_b128 v249, v[50:53]
	s_waitcnt vmcnt(2)
	ds_write_b128 v250, v[66:69]
	s_waitcnt vmcnt(1)
	ds_write_b128 v0, v[70:73] offset:36864
	v_add_u32_e32 v0, v235, v238
	v_mov_b32_e32 v20, v1
	v_mov_b32_e32 v21, v1
	s_waitcnt vmcnt(0)
	ds_write_b128 v0, v[74:77] offset:36864
	v_mov_b32_e32 v0, v1
	v_mov_b32_e32 v18, v1
	v_mov_b32_e32 v19, v1
	v_mov_b64_e32 v[24:25], v[20:21]
	v_mov_b64_e32 v[32:33], v[20:21]
	v_mov_b64_e32 v[44:45], v[20:21]
	v_mov_b64_e32 v[52:53], v[20:21]
	v_mov_b64_e32 v[60:61], v[20:21]
	v_mov_b64_e32 v[68:69], v[20:21]
	v_mov_b64_e32 v[76:77], v[20:21]
	v_mov_b64_e32 v[84:85], v[20:21]
	v_mov_b64_e32 v[92:93], v[20:21]
	v_mov_b64_e32 v[100:101], v[20:21]
	v_mov_b64_e32 v[108:109], v[20:21]
	v_mov_b64_e32 v[116:117], v[20:21]
	v_mov_b64_e32 v[124:125], v[20:21]
	v_mov_b64_e32 v[132:133], v[20:21]
	v_mov_b64_e32 v[140:141], v[20:21]
	v_mov_b64_e32 v[28:29], v[20:21]
	v_mov_b64_e32 v[36:37], v[20:21]
	v_mov_b64_e32 v[40:41], v[20:21]
	v_mov_b64_e32 v[48:49], v[20:21]
	v_mov_b64_e32 v[56:57], v[20:21]
	v_mov_b64_e32 v[64:65], v[20:21]
	v_mov_b64_e32 v[72:73], v[20:21]
	v_mov_b64_e32 v[80:81], v[20:21]
	v_mov_b64_e32 v[88:89], v[20:21]
	v_mov_b64_e32 v[96:97], v[20:21]
	v_mov_b64_e32 v[104:105], v[20:21]
	v_mov_b64_e32 v[112:113], v[20:21]
	v_mov_b64_e32 v[120:121], v[20:21]
	v_mov_b64_e32 v[128:129], v[20:21]
	v_mov_b64_e32 v[136:137], v[20:21]
	v_mov_b64_e32 v[144:145], v[20:21]
	v_mov_b64_e32 v[22:23], v[18:19]
	v_mov_b64_e32 v[30:31], v[18:19]
	v_mov_b64_e32 v[42:43], v[18:19]
	v_mov_b64_e32 v[50:51], v[18:19]
	v_mov_b64_e32 v[58:59], v[18:19]
	v_mov_b64_e32 v[66:67], v[18:19]
	v_mov_b64_e32 v[74:75], v[18:19]
	v_mov_b64_e32 v[82:83], v[18:19]
	v_mov_b64_e32 v[90:91], v[18:19]
	v_mov_b64_e32 v[98:99], v[18:19]
	v_mov_b64_e32 v[106:107], v[18:19]
	v_mov_b64_e32 v[114:115], v[18:19]
	v_mov_b64_e32 v[122:123], v[18:19]
	v_mov_b64_e32 v[130:131], v[18:19]
	v_mov_b64_e32 v[138:139], v[18:19]
	v_mov_b64_e32 v[26:27], v[18:19]
	v_mov_b64_e32 v[34:35], v[18:19]
	v_mov_b64_e32 v[38:39], v[18:19]
	v_mov_b64_e32 v[46:47], v[18:19]
	v_mov_b64_e32 v[54:55], v[18:19]
	v_mov_b64_e32 v[62:63], v[18:19]
	v_mov_b64_e32 v[70:71], v[18:19]
	v_mov_b64_e32 v[78:79], v[18:19]
	v_mov_b64_e32 v[86:87], v[18:19]
	v_mov_b64_e32 v[94:95], v[18:19]
	v_mov_b64_e32 v[102:103], v[18:19]
	v_mov_b64_e32 v[110:111], v[18:19]
	v_mov_b64_e32 v[118:119], v[18:19]
	v_mov_b64_e32 v[126:127], v[18:19]
	v_mov_b64_e32 v[134:135], v[18:19]
	v_mov_b64_e32 v[142:143], v[18:19]
	v_mov_b64_e32 v[218:219], v[0:1]
	s_waitcnt lgkmcnt(0)
	s_barrier
	s_branch .LBB0_595

; #define LAS __attribute__((address_space(3)))
; __device__ __forceinline__ f32x4 mma16(bf16x8 a, bf16x8 b, f32x4 c) { return __builtin_amdgcn_mfma_f32_16x16x32_bf16(a, b, c, 0, 0, 0); }
; __device__ __forceinline__ void attn_phase(LAS unsigned char* lds, const bf16_t* proj, bf16_t* oa, const float* lamp, const float* subg, const float* relb, const float* qg, int wg, int tid) {
;     ...
;         for (int kt = 0; kt < nkt; ++kt) {
;             const int cur = kt & 1, k0 = kt * 32; const bool more = kt + 1 < nkt;
;             u32x4 kr[2], vr[2];
;             if (more) {
; #pragma unroll
;                 for (int i = 0; i < 2; ++i) { const int id = tid + 512 * i, s = id >> 9, row = (id >> 4) & 31, ch = id & 15; kr[i] = *(const u32x4*)(ksrc + (size_t)(k0 + 32 + row) * DIFF_IN + s * 128 + ch * 8); }
; #pragma unroll
;                 for (int i = 0; i < 2; ++i) { const int id = tid + 512 * i, row = id >> 5, ch = id & 31; vr[i] = *(const u32x4*)(vsrc + (size_t)(k0 + 32 + row) * DIFF_IN + ch * 8); }
;             }
;             if (k0 <= qw0 + 15) {
;                 const LAS bf16_t* Kc = Kb + cur * KB_BUF; const LAS bf16_t* Vc = Vb + cur * VB_BUF;
;                 const bool far = (qw0 - (k0 + 31)) >= 128;
;                 f32x4 st[2][2];
;                 int qoff = (fr * KP + 8 * fq); asm volatile("" : "+v"(qoff));
; #pragma unroll
;                 for (int s = 0; s < 2; ++s) { const float ini = far ? (s ? c31b : c31a) : 0.f;
;                     st[s][0] = (f32x4){ini, ini, ini, ini}; st[s][1] = st[s][0];
; #pragma unroll
;                     for (int ks = 0; ks < 4; ++ks) { const bf16x8 qfr = *(const LAS bf16x8*)(Qw + s * 16 * KP + qoff + 32 * ks);
; #pragma unroll
;                         for (int T = 0; T < 2; ++T) st[s][T] = mma16(frag_rowk(Kc + s * 32 * KP, KP, 16 * T, 32 * ks, fr, fq), qfr, st[s][T]); } }
.LBB0_595:
	s_cmp_lt_u32 s33, s34
	s_cselect_b64 s[20:21], -1, 0
	s_cmp_ge_u32 s33, s34
	s_cselect_b64 s[0:1], -1, 0
	s_add_i32 s30, s33, -1
	s_and_b32 s46, s30, 1
	s_cmp_gt_i32 s37, s35
	s_cbranch_scc0 .Lat_compute
	s_andn2_b64 vcc, exec, s[20:21]
	s_cbranch_vccnz .LBB0_594
	v_lshl_add_u64 v[2:3], v[206:207], 0, s[100:101]
	v_lshl_add_u64 v[6:7], v[208:209], 0, s[100:101]
	v_lshl_add_u64 v[10:11], v[204:205], 0, s[100:101]
	v_lshl_add_u64 v[14:15], v[202:203], 0, s[100:101]
	global_load_dwordx4 v[2:5], v[2:3], off
	s_nop 0
	global_load_dwordx4 v[6:9], v[6:7], off
	s_nop 0
	global_load_dwordx4 v[10:13], v[10:11], off
	s_nop 0
	global_load_dwordx4 v[14:17], v[14:15], off
	s_branch .LBB0_634
.Lat_compute:
	v_lshl_add_u32 v0, v236, 1, s44
	s_mul_i32 s30, s46, 0x4800
	v_add_u32_e32 v224, s30, v245
	ds_read_b128 v[2:5], v0
	ds_read_b128 v[6:9], v224
	ds_read_b128 v[10:13], v224 offset:4608
	ds_read_b128 v[14:17], v0 offset:64
	ds_read_b128 v[162:165], v224 offset:64
	ds_read_b128 v[220:223], v224 offset:4672
	s_cmpk_gt_i32 s36, 0x7f
	s_cselect_b64 vcc, -1, 0
	v_cndmask_b32_e32 v228, 0, v243, vcc
	v_mov_b32_e32 v229, v228
	v_mov_b32_e32 v230, v228
	v_mov_b32_e32 v231, v228
	s_waitcnt lgkmcnt(3)
	s_nop 1
	v_mfma_f32_16x16x32_bf16 v[146:149], v[6:9], v[2:5], v[228:231]
	v_mfma_f32_16x16x32_bf16 v[150:153], v[10:13], v[2:5], v[228:231]
	ds_read_b128 v[2:5], v0 offset:128
	ds_read_b128 v[6:9], v224 offset:128
	ds_read_b128 v[10:13], v224 offset:4736
	s_waitcnt lgkmcnt(3)
	v_mfma_f32_16x16x32_bf16 v[146:149], v[162:165], v[14:17], v[146:149]
	v_mfma_f32_16x16x32_bf16 v[150:153], v[220:223], v[14:17], v[150:153]
	ds_read_b128 v[14:17], v0 offset:192
	ds_read_b128 v[162:165], v224 offset:192
	ds_read_b128 v[220:223], v224 offset:4800
	s_waitcnt lgkmcnt(3)
	v_mfma_f32_16x16x32_bf16 v[146:149], v[6:9], v[2:5], v[146:149]
	v_mfma_f32_16x16x32_bf16 v[150:153], v[10:13], v[2:5], v[150:153]
	ds_read_b128 v[2:5], v0 offset:4608
	ds_read_b128 v[6:9], v224 offset:9216
	ds_read_b128 v[10:13], v224 offset:13824
	s_waitcnt lgkmcnt(3)
	v_mfma_f32_16x16x32_bf16 v[146:149], v[162:165], v[14:17], v[146:149]
	v_mfma_f32_16x16x32_bf16 v[150:153], v[220:223], v[14:17], v[150:153]
	ds_read_b128 v[14:17], v0 offset:4672
	ds_read_b128 v[162:165], v224 offset:9280
	ds_read_b128 v[220:223], v224 offset:13888
	v_cndmask_b32_e32 v228, 0, v244, vcc
	v_mov_b32_e32 v229, v228
	v_mov_b32_e32 v230, v228
	v_mov_b32_e32 v231, v228
	s_waitcnt lgkmcnt(3)
	s_nop 1
	v_mfma_f32_16x16x32_bf16 v[158:161], v[6:9], v[2:5], v[228:231]
	v_mfma_f32_16x16x32_bf16 v[154:157], v[10:13], v[2:5], v[228:231]
	ds_read_b128 v[2:5], v0 offset:4736
	ds_read_b128 v[6:9], v224 offset:9344
	ds_read_b128 v[10:13], v224 offset:13952
	s_waitcnt lgkmcnt(3)
	v_mfma_f32_16x16x32_bf16 v[158:161], v[162:165], v[14:17], v[158:161]
	v_mfma_f32_16x16x32_bf16 v[154:157], v[220:223], v[14:17], v[154:157]
	ds_read_b128 v[14:17], v0 offset:4800
	ds_read_b128 v[162:165], v224 offset:9408
	ds_read_b128 v[220:223], v224 offset:14016
	s_waitcnt lgkmcnt(3)
	v_mfma_f32_16x16x32_bf16 v[158:161], v[6:9], v[2:5], v[158:161]
	v_mfma_f32_16x16x32_bf16 v[154:157], v[10:13], v[2:5], v[154:157]
	s_waitcnt lgkmcnt(0)
	v_mfma_f32_16x16x32_bf16 v[158:161], v[162:165], v[14:17], v[158:161]
	v_mfma_f32_16x16x32_bf16 v[154:157], v[220:223], v[14:17], v[154:157]
	s_and_b64 s[98:99], s[20:21], exec
	s_cbranch_scc0 .Lat_noload
	v_lshl_add_u64 v[2:3], v[206:207], 0, s[100:101]
	v_lshl_add_u64 v[6:7], v[208:209], 0, s[100:101]
	v_lshl_add_u64 v[10:11], v[204:205], 0, s[100:101]
	v_lshl_add_u64 v[14:15], v[202:203], 0, s[100:101]
	global_load_dwordx4 v[2:5], v[2:3], off
	s_nop 0
	global_load_dwordx4 v[6:9], v[6:7], off
	s_nop 0
	global_load_dwordx4 v[10:13], v[10:11], off
	s_nop 0
	global_load_dwordx4 v[14:17], v[14:15], off

; __device__ __forceinline__ unsigned cvtpk(float lo, float hi) { return pg8::cvt_pk_bf16(lo, hi); }
; __device__ __forceinline__ f32x4 mma16(bf16x8 a, bf16x8 b, f32x4 c) { return __builtin_amdgcn_mfma_f32_16x16x32_bf16(a, b, c, 0, 0, 0); }
; __device__ __forceinline__ void attn_phase(LAS unsigned char* lds, const bf16_t* proj, bf16_t* oa, const float* lamp, const float* subg, const float* relb, const float* qg, int wg, int tid) {
;     ...
;                 bf16x8 pf[2];
; #pragma unroll
;                 for (int s = 0; s < 2; ++s) { float ps = 0.f;
; #pragma unroll
;                     for (int T = 0; T < 2; ++T)
; #pragma unroll
;                         for (int r = 0; r < 4; ++r) { const float p = __builtin_amdgcn_exp2f(st[s][T][r]); st[s][T][r] = p; ps += p; }
;                     if (s == 0) l0 += ps; else l1 += ps;
;                     u32x4 w; w.x = cvtpk(st[s][0][0], st[s][0][1]); w.y = cvtpk(st[s][0][2], st[s][0][3]); w.z = cvtpk(st[s][1][0], st[s][1][1]); w.w = cvtpk(st[s][1][2], st[s][1][3]);
;                     pf[s] = __builtin_bit_cast(bf16x8, w); }
; #pragma unroll
;                 for (int vt = 0; vt < 16; ++vt) { const bf16x8 vf = frag_tr2(Vc, VP, 4 * fq, 16 + 4 * fq, 16 * vt, fr);
;                     o[0][vt] = mma16(vf, pf[0], o[0][vt]); o[1][vt] = mma16(vf, pf[1], o[1][vt]); }
;             }
.LBB0_633:
	s_mul_i32 s30, s46, 0x4400
	v_add_u32_e32 v0, s30, v246
	v_exp_f32_e32 v231, v146
	v_exp_f32_e32 v229, v147
	v_exp_f32_e32 v227, v148
	v_exp_f32_e32 v225, v149
	v_exp_f32_e32 v223, v150
	v_exp_f32_e32 v221, v151
	v_exp_f32_e32 v165, v152
	v_exp_f32_e32 v163, v153
	v_exp_f32_e32 v230, v158
	v_exp_f32_e32 v228, v159
	v_exp_f32_e32 v226, v160
	v_exp_f32_e32 v224, v161
	v_exp_f32_e32 v222, v154
	v_exp_f32_e32 v220, v155
	v_exp_f32_e32 v164, v156
	v_exp_f32_e32 v162, v157
	ds_read_b64_tr_b16 v[158:159], v0 offset:36864
	ds_read_b64_tr_b16 v[160:161], v0 offset:45568
	ds_read_b64_tr_b16 v[154:155], v0 offset:36896
	ds_read_b64_tr_b16 v[156:157], v0 offset:45600
	ds_read_b64_tr_b16 v[210:211], v0 offset:36928
	ds_read_b64_tr_b16 v[212:213], v0 offset:45632
	ds_read_b64_tr_b16 v[214:215], v0 offset:36960
	ds_read_b64_tr_b16 v[216:217], v0 offset:45664
	v_cvt_pk_bf16_f32 v146, v231, v229
	v_cvt_pk_bf16_f32 v147, v227, v225
	v_cvt_pk_bf16_f32 v148, v223, v221
	v_cvt_pk_bf16_f32 v149, v165, v163
	v_cvt_pk_bf16_f32 v150, v230, v228
	v_cvt_pk_bf16_f32 v151, v226, v224
	v_cvt_pk_bf16_f32 v152, v222, v220
	v_cvt_pk_bf16_f32 v153, v164, v162
	v_add_f32_e64 v230, v230, 0
	v_add_f32_e64 v231, v231, 0
	v_pk_add_f32 v[228:229], v[228:229], v[230:231]
	v_pk_add_f32 v[226:227], v[226:227], v[228:229]
	v_add_f32_e64 v226, v224, v226
	v_add_f32_e64 v227, v225, v227
	v_pk_add_f32 v[226:227], v[222:223], v[226:227]
	v_add_f32_e64 v226, v220, v226
	v_add_f32_e64 v227, v221, v227
	v_pk_add_f32 v[226:227], v[164:165], v[226:227]
	v_add_f32_e64 v226, v162, v226
	v_add_f32_e64 v227, v163, v227
	v_pk_add_f32 v[218:219], v[218:219], v[226:227]
	ds_read_b64_tr_b16 v[162:163], v0 offset:36992
	ds_read_b64_tr_b16 v[164:165], v0 offset:45696
	ds_read_b64_tr_b16 v[220:221], v0 offset:37024
	ds_read_b64_tr_b16 v[222:223], v0 offset:45728
	ds_read_b64_tr_b16 v[224:225], v0 offset:37056
	ds_read_b64_tr_b16 v[226:227], v0 offset:45760
	ds_read_b64_tr_b16 v[228:229], v0 offset:37088
	ds_read_b64_tr_b16 v[230:231], v0 offset:45792
	s_waitcnt lgkmcnt(14)
	v_mfma_f32_16x16x32_bf16 v[142:145], v[158:161], v[146:149], v[142:145]
	v_mfma_f32_16x16x32_bf16 v[138:141], v[158:161], v[150:153], v[138:141]
	ds_read_b64_tr_b16 v[158:159], v0 offset:37120
	ds_read_b64_tr_b16 v[160:161], v0 offset:45824
	s_waitcnt lgkmcnt(14)
	v_mfma_f32_16x16x32_bf16 v[134:137], v[154:157], v[146:149], v[134:137]
	v_mfma_f32_16x16x32_bf16 v[130:133], v[154:157], v[150:153], v[130:133]
	ds_read_b64_tr_b16 v[154:155], v0 offset:37152
	ds_read_b64_tr_b16 v[156:157], v0 offset:45856
	s_waitcnt lgkmcnt(14)
	v_mfma_f32_16x16x32_bf16 v[126:129], v[210:213], v[146:149], v[126:129]
	v_mfma_f32_16x16x32_bf16 v[122:125], v[210:213], v[150:153], v[122:125]
	ds_read_b64_tr_b16 v[210:211], v0 offset:37184
	ds_read_b64_tr_b16 v[212:213], v0 offset:45888
	s_waitcnt lgkmcnt(14)
	v_mfma_f32_16x16x32_bf16 v[118:121], v[214:217], v[146:149], v[118:121]
	v_mfma_f32_16x16x32_bf16 v[114:117], v[214:217], v[150:153], v[114:117]
	ds_read_b64_tr_b16 v[214:215], v0 offset:37216
	ds_read_b64_tr_b16 v[216:217], v0 offset:45920
	s_waitcnt lgkmcnt(14)
	v_mfma_f32_16x16x32_bf16 v[110:113], v[162:165], v[146:149], v[110:113]
	v_mfma_f32_16x16x32_bf16 v[106:109], v[162:165], v[150:153], v[106:109]
	ds_read_b64_tr_b16 v[162:163], v0 offset:37248
	ds_read_b64_tr_b16 v[164:165], v0 offset:45952
	s_waitcnt lgkmcnt(14)
	v_mfma_f32_16x16x32_bf16 v[102:105], v[220:223], v[146:149], v[102:105]
	v_mfma_f32_16x16x32_bf16 v[98:101], v[220:223], v[150:153], v[98:101]
	ds_read_b64_tr_b16 v[220:221], v0 offset:37280
	ds_read_b64_tr_b16 v[222:223], v0 offset:45984
	s_waitcnt lgkmcnt(14)
	v_mfma_f32_16x16x32_bf16 v[94:97], v[224:227], v[146:149], v[94:97]
	v_mfma_f32_16x16x32_bf16 v[90:93], v[224:227], v[150:153], v[90:93]
	ds_read_b64_tr_b16 v[224:225], v0 offset:37312
	ds_read_b64_tr_b16 v[226:227], v0 offset:46016
	s_waitcnt lgkmcnt(14)
	v_mfma_f32_16x16x32_bf16 v[86:89], v[228:231], v[146:149], v[86:89]
	v_mfma_f32_16x16x32_bf16 v[82:85], v[228:231], v[150:153], v[82:85]
	ds_read_b64_tr_b16 v[228:229], v0 offset:37344
	ds_read_b64_tr_b16 v[230:231], v0 offset:46048
	s_waitcnt lgkmcnt(14)
	v_mfma_f32_16x16x32_bf16 v[78:81], v[158:161], v[146:149], v[78:81]
	v_mfma_f32_16x16x32_bf16 v[74:77], v[158:161], v[150:153], v[74:77]
	s_waitcnt lgkmcnt(12)
	v_mfma_f32_16x16x32_bf16 v[70:73], v[154:157], v[146:149], v[70:73]
	v_mfma_f32_16x16x32_bf16 v[66:69], v[154:157], v[150:153], v[66:69]
	s_waitcnt lgkmcnt(10)
	v_mfma_f32_16x16x32_bf16 v[62:65], v[210:213], v[146:149], v[62:65]
	v_mfma_f32_16x16x32_bf16 v[58:61], v[210:213], v[150:153], v[58:61]
	s_waitcnt lgkmcnt(8)
	v_mfma_f32_16x16x32_bf16 v[54:57], v[214:217], v[146:149], v[54:57]
	v_mfma_f32_16x16x32_bf16 v[50:53], v[214:217], v[150:153], v[50:53]
	s_waitcnt lgkmcnt(6)
	v_mfma_f32_16x16x32_bf16 v[46:49], v[162:165], v[146:149], v[46:49]
	v_mfma_f32_16x16x32_bf16 v[42:45], v[162:165], v[150:153], v[42:45]
	s_waitcnt lgkmcnt(4)
	v_mfma_f32_16x16x32_bf16 v[38:41], v[220:223], v[146:149], v[38:41]
	v_mfma_f32_16x16x32_bf16 v[30:33], v[220:223], v[150:153], v[30:33]
	s_waitcnt lgkmcnt(2)
	v_mfma_f32_16x16x32_bf16 v[34:37], v[224:227], v[146:149], v[34:37]
	v_mfma_f32_16x16x32_bf16 v[22:25], v[224:227], v[150:153], v[22:25]
	s_waitcnt lgkmcnt(0)
	v_mfma_f32_16x16x32_bf16 v[26:29], v[228:231], v[146:149], v[26:29]
	v_mfma_f32_16x16x32_bf16 v[18:21], v[228:231], v[150:153], v[18:21]
	s_andn2_b64 vcc, exec, s[20:21]
	s_cbranch_vccnz .LBB0_594
